# conv epilogue v2: 16-byte write-through stores of both column halves, boundary rows reloaded just in time (8 fewer VGPRs)
# speedup vs baseline: 1.0948x; 1.0032x over previous
.Lce_nobar0:
	ds_read_b128 v[164:167], v222 offset:0
	ds_read_b128 v[168:171], v222 offset:512
	s_waitcnt vmcnt(4)
	v_fma_f32 v208, v120, v152, v128
	v_fma_f32 v209, v121, v153, v129
	v_fma_f32 v210, v122, v154, v130
	v_fma_f32 v211, v123, v155, v131
	v_fmac_f32_dpp v208, v152, v116 row_shr:1 row_mask:0xf bank_mask:0xf
	v_fmac_f32_dpp v209, v153, v117 row_shr:1 row_mask:0xf bank_mask:0xf
	v_fmac_f32_dpp v210, v154, v118 row_shr:1 row_mask:0xf bank_mask:0xf
	v_fmac_f32_dpp v211, v155, v119 row_shr:1 row_mask:0xf bank_mask:0xf
	v_fmac_f32_dpp v208, v152, v124 row_shl:1 row_mask:0xf bank_mask:0xf
	v_fmac_f32_dpp v209, v153, v125 row_shl:1 row_mask:0xf bank_mask:0xf
	v_fmac_f32_dpp v210, v154, v126 row_shl:1 row_mask:0xf bank_mask:0xf
	v_fmac_f32_dpp v211, v155, v127 row_shl:1 row_mask:0xf bank_mask:0xf
	v_fmac_f32_dpp v208, v160, v116 row_shl:15 row_mask:0xf bank_mask:0xf
	v_fmac_f32_dpp v209, v161, v117 row_shl:15 row_mask:0xf bank_mask:0xf
	v_fmac_f32_dpp v210, v162, v118 row_shl:15 row_mask:0xf bank_mask:0xf
	v_fmac_f32_dpp v211, v163, v119 row_shl:15 row_mask:0xf bank_mask:0xf
	v_fmac_f32_dpp v208, v112, v124 row_shr:15 row_mask:0xf bank_mask:0xf
	v_fmac_f32_dpp v209, v113, v125 row_shr:15 row_mask:0xf bank_mask:0xf
	v_fmac_f32_dpp v210, v114, v126 row_shr:15 row_mask:0xf bank_mask:0xf
	v_fmac_f32_dpp v211, v115, v127 row_shr:15 row_mask:0xf bank_mask:0xf
	v_fma_f32 v212, v136, v148, v144
	v_fma_f32 v213, v137, v149, v145
	v_fma_f32 v214, v138, v150, v146
	v_fma_f32 v215, v139, v151, v147
	v_fmac_f32_dpp v212, v148, v132 row_shr:1 row_mask:0xf bank_mask:0xf
	v_fmac_f32_dpp v213, v149, v133 row_shr:1 row_mask:0xf bank_mask:0xf
	v_fmac_f32_dpp v214, v150, v134 row_shr:1 row_mask:0xf bank_mask:0xf
	v_fmac_f32_dpp v215, v151, v135 row_shr:1 row_mask:0xf bank_mask:0xf
	v_fmac_f32_dpp v212, v148, v140 row_shl:1 row_mask:0xf bank_mask:0xf
	v_fmac_f32_dpp v213, v149, v141 row_shl:1 row_mask:0xf bank_mask:0xf
	v_fmac_f32_dpp v214, v150, v142 row_shl:1 row_mask:0xf bank_mask:0xf
	v_fmac_f32_dpp v215, v151, v143 row_shl:1 row_mask:0xf bank_mask:0xf
	v_fmac_f32_dpp v212, v156, v132 row_shl:15 row_mask:0xf bank_mask:0xf
	v_fmac_f32_dpp v213, v157, v133 row_shl:15 row_mask:0xf bank_mask:0xf
	v_fmac_f32_dpp v214, v158, v134 row_shl:15 row_mask:0xf bank_mask:0xf
	v_fmac_f32_dpp v215, v159, v135 row_shl:15 row_mask:0xf bank_mask:0xf
	v_fmac_f32_dpp v212, v108, v140 row_shr:15 row_mask:0xf bank_mask:0xf
	v_fmac_f32_dpp v213, v109, v141 row_shr:15 row_mask:0xf bank_mask:0xf
	v_fmac_f32_dpp v214, v110, v142 row_shr:15 row_mask:0xf bank_mask:0xf
	v_fmac_f32_dpp v215, v111, v143 row_shr:15 row_mask:0xf bank_mask:0xf
	v_mul_f32_e32 v216, 0xbfb8aa3b, v208
	v_mul_f32_e32 v217, 0xbfb8aa3b, v209
	v_mul_f32_e32 v218, 0xbfb8aa3b, v210
	v_mul_f32_e32 v219, 0xbfb8aa3b, v211
	v_exp_f32_e32 v216, v216
	v_exp_f32_e32 v217, v217
	v_exp_f32_e32 v218, v218
	v_exp_f32_e32 v219, v219
	v_add_f32_e32 v216, 1.0, v216
	v_add_f32_e32 v217, 1.0, v217
	v_add_f32_e32 v218, 1.0, v218
	v_add_f32_e32 v219, 1.0, v219
	v_rcp_f32_e32 v216, v216
	v_rcp_f32_e32 v217, v217
	v_rcp_f32_e32 v218, v218
	v_rcp_f32_e32 v219, v219
	v_mul_f32_e32 v208, v208, v216
	v_mul_f32_e32 v209, v209, v217
	v_mul_f32_e32 v210, v210, v218
	v_mul_f32_e32 v211, v211, v219
	v_mul_f32_e32 v208, v208, v212
	v_mul_f32_e32 v209, v209, v213
	v_mul_f32_e32 v210, v210, v214
	v_mul_f32_e32 v211, v211, v215
	v_cvt_pk_bf16_f32 v174, v208, v209
	v_cvt_pk_bf16_f32 v175, v210, v211
	v_fma_f32 v208, v120, v112, v128
	v_fma_f32 v209, v121, v113, v129
	v_fma_f32 v210, v122, v114, v130
	v_fma_f32 v211, v123, v115, v131
	v_fmac_f32_dpp v208, v112, v116 row_shr:1 row_mask:0xf bank_mask:0xf
	v_fmac_f32_dpp v209, v113, v117 row_shr:1 row_mask:0xf bank_mask:0xf
	v_fmac_f32_dpp v210, v114, v118 row_shr:1 row_mask:0xf bank_mask:0xf
	v_fmac_f32_dpp v211, v115, v119 row_shr:1 row_mask:0xf bank_mask:0xf
	v_fmac_f32_dpp v208, v112, v124 row_shl:1 row_mask:0xf bank_mask:0xf
	v_fmac_f32_dpp v209, v113, v125 row_shl:1 row_mask:0xf bank_mask:0xf
	v_fmac_f32_dpp v210, v114, v126 row_shl:1 row_mask:0xf bank_mask:0xf
	v_fmac_f32_dpp v211, v115, v127 row_shl:1 row_mask:0xf bank_mask:0xf
	v_fmac_f32_dpp v208, v152, v116 row_shl:15 row_mask:0xf bank_mask:0xf
	v_fmac_f32_dpp v209, v153, v117 row_shl:15 row_mask:0xf bank_mask:0xf
	v_fmac_f32_dpp v210, v154, v118 row_shl:15 row_mask:0xf bank_mask:0xf
	v_fmac_f32_dpp v211, v155, v119 row_shl:15 row_mask:0xf bank_mask:0xf
	v_fmac_f32_dpp v208, v100, v124 row_shr:15 row_mask:0xf bank_mask:0xf
	v_fmac_f32_dpp v209, v101, v125 row_shr:15 row_mask:0xf bank_mask:0xf
	v_fmac_f32_dpp v210, v102, v126 row_shr:15 row_mask:0xf bank_mask:0xf
	v_fmac_f32_dpp v211, v103, v127 row_shr:15 row_mask:0xf bank_mask:0xf
	v_fma_f32 v212, v136, v108, v144
	v_fma_f32 v213, v137, v109, v145
	v_fma_f32 v214, v138, v110, v146
	v_fma_f32 v215, v139, v111, v147
	v_fmac_f32_dpp v212, v108, v132 row_shr:1 row_mask:0xf bank_mask:0xf
	v_fmac_f32_dpp v213, v109, v133 row_shr:1 row_mask:0xf bank_mask:0xf
	v_fmac_f32_dpp v214, v110, v134 row_shr:1 row_mask:0xf bank_mask:0xf
	v_fmac_f32_dpp v215, v111, v135 row_shr:1 row_mask:0xf bank_mask:0xf
	v_fmac_f32_dpp v212, v108, v140 row_shl:1 row_mask:0xf bank_mask:0xf
	v_fmac_f32_dpp v213, v109, v141 row_shl:1 row_mask:0xf bank_mask:0xf
	v_fmac_f32_dpp v214, v110, v142 row_shl:1 row_mask:0xf bank_mask:0xf
	v_fmac_f32_dpp v215, v111, v143 row_shl:1 row_mask:0xf bank_mask:0xf
	v_fmac_f32_dpp v212, v148, v132 row_shl:15 row_mask:0xf bank_mask:0xf
	v_fmac_f32_dpp v213, v149, v133 row_shl:15 row_mask:0xf bank_mask:0xf
	v_fmac_f32_dpp v214, v150, v134 row_shl:15 row_mask:0xf bank_mask:0xf
	v_fmac_f32_dpp v215, v151, v135 row_shl:15 row_mask:0xf bank_mask:0xf
	v_fmac_f32_dpp v212, v104, v140 row_shr:15 row_mask:0xf bank_mask:0xf
	v_fmac_f32_dpp v213, v105, v141 row_shr:15 row_mask:0xf bank_mask:0xf
	v_fmac_f32_dpp v214, v106, v142 row_shr:15 row_mask:0xf bank_mask:0xf
	v_fmac_f32_dpp v215, v107, v143 row_shr:15 row_mask:0xf bank_mask:0xf
	v_mul_f32_e32 v216, 0xbfb8aa3b, v208
	v_mul_f32_e32 v217, 0xbfb8aa3b, v209
	v_mul_f32_e32 v218, 0xbfb8aa3b, v210
	v_mul_f32_e32 v219, 0xbfb8aa3b, v211
	v_exp_f32_e32 v216, v216
	v_exp_f32_e32 v217, v217
	v_exp_f32_e32 v218, v218
	v_exp_f32_e32 v219, v219
	v_add_f32_e32 v216, 1.0, v216
	v_add_f32_e32 v217, 1.0, v217
	v_add_f32_e32 v218, 1.0, v218
	v_add_f32_e32 v219, 1.0, v219
	v_rcp_f32_e32 v216, v216
	v_rcp_f32_e32 v217, v217
	v_rcp_f32_e32 v218, v218
	v_rcp_f32_e32 v219, v219
	v_mul_f32_e32 v208, v208, v216
	v_mul_f32_e32 v209, v209, v217
	v_mul_f32_e32 v210, v210, v218
	v_mul_f32_e32 v211, v211, v219
	v_mul_f32_e32 v208, v208, v212
	v_mul_f32_e32 v209, v209, v213
	v_mul_f32_e32 v210, v210, v214
	v_mul_f32_e32 v211, v211, v215
	v_cvt_pk_bf16_f32 v176, v208, v209
	v_cvt_pk_bf16_f32 v177, v210, v211
	s_waitcnt lgkmcnt(0)
	v_fma_f32 v208, v120, v160, v128
	v_fma_f32 v209, v121, v161, v129
	v_fma_f32 v210, v122, v162, v130
	v_fma_f32 v211, v123, v163, v131
	v_fmac_f32_dpp v208, v160, v116 row_shr:1 row_mask:0xf bank_mask:0xf
	v_fmac_f32_dpp v209, v161, v117 row_shr:1 row_mask:0xf bank_mask:0xf
	v_fmac_f32_dpp v210, v162, v118 row_shr:1 row_mask:0xf bank_mask:0xf
	v_fmac_f32_dpp v211, v163, v119 row_shr:1 row_mask:0xf bank_mask:0xf
	v_fmac_f32_dpp v208, v160, v124 row_shl:1 row_mask:0xf bank_mask:0xf
	v_fmac_f32_dpp v209, v161, v125 row_shl:1 row_mask:0xf bank_mask:0xf
	v_fmac_f32_dpp v210, v162, v126 row_shl:1 row_mask:0xf bank_mask:0xf
	v_fmac_f32_dpp v211, v163, v127 row_shl:1 row_mask:0xf bank_mask:0xf
	v_fmac_f32_dpp v208, v164, v116 row_shl:15 row_mask:0xf bank_mask:0xf
	v_fmac_f32_dpp v209, v165, v117 row_shl:15 row_mask:0xf bank_mask:0xf
	v_fmac_f32_dpp v210, v166, v118 row_shl:15 row_mask:0xf bank_mask:0xf
	v_fmac_f32_dpp v211, v167, v119 row_shl:15 row_mask:0xf bank_mask:0xf
	v_fmac_f32_dpp v208, v152, v124 row_shr:15 row_mask:0xf bank_mask:0xf
	v_fmac_f32_dpp v209, v153, v125 row_shr:15 row_mask:0xf bank_mask:0xf
	v_fmac_f32_dpp v210, v154, v126 row_shr:15 row_mask:0xf bank_mask:0xf
	v_fmac_f32_dpp v211, v155, v127 row_shr:15 row_mask:0xf bank_mask:0xf
	v_fma_f32 v212, v136, v156, v144
	v_fma_f32 v213, v137, v157, v145
	v_fma_f32 v214, v138, v158, v146
	v_fma_f32 v215, v139, v159, v147
	v_fmac_f32_dpp v212, v156, v132 row_shr:1 row_mask:0xf bank_mask:0xf
	v_fmac_f32_dpp v213, v157, v133 row_shr:1 row_mask:0xf bank_mask:0xf
	v_fmac_f32_dpp v214, v158, v134 row_shr:1 row_mask:0xf bank_mask:0xf
	v_fmac_f32_dpp v215, v159, v135 row_shr:1 row_mask:0xf bank_mask:0xf
	v_fmac_f32_dpp v212, v156, v140 row_shl:1 row_mask:0xf bank_mask:0xf
	v_fmac_f32_dpp v213, v157, v141 row_shl:1 row_mask:0xf bank_mask:0xf
	v_fmac_f32_dpp v214, v158, v142 row_shl:1 row_mask:0xf bank_mask:0xf
	v_fmac_f32_dpp v215, v159, v143 row_shl:1 row_mask:0xf bank_mask:0xf
	v_fmac_f32_dpp v212, v168, v132 row_shl:15 row_mask:0xf bank_mask:0xf
	v_fmac_f32_dpp v213, v169, v133 row_shl:15 row_mask:0xf bank_mask:0xf
	v_fmac_f32_dpp v214, v170, v134 row_shl:15 row_mask:0xf bank_mask:0xf
	v_fmac_f32_dpp v215, v171, v135 row_shl:15 row_mask:0xf bank_mask:0xf
	v_fmac_f32_dpp v212, v148, v140 row_shr:15 row_mask:0xf bank_mask:0xf
	v_fmac_f32_dpp v213, v149, v141 row_shr:15 row_mask:0xf bank_mask:0xf
	v_fmac_f32_dpp v214, v150, v142 row_shr:15 row_mask:0xf bank_mask:0xf
	v_fmac_f32_dpp v215, v151, v143 row_shr:15 row_mask:0xf bank_mask:0xf
	ds_read_b128 v[164:167], v221 offset:2048
	ds_read_b128 v[168:171], v221 offset:2560
	v_mul_f32_e32 v216, 0xbfb8aa3b, v208
	v_mul_f32_e32 v217, 0xbfb8aa3b, v209
	v_mul_f32_e32 v218, 0xbfb8aa3b, v210
	v_mul_f32_e32 v219, 0xbfb8aa3b, v211
	v_exp_f32_e32 v216, v216
	v_exp_f32_e32 v217, v217
	v_exp_f32_e32 v218, v218
	v_exp_f32_e32 v219, v219
	v_add_f32_e32 v216, 1.0, v216
	v_add_f32_e32 v217, 1.0, v217
	v_add_f32_e32 v218, 1.0, v218
	v_add_f32_e32 v219, 1.0, v219
	v_rcp_f32_e32 v216, v216
	v_rcp_f32_e32 v217, v217
	v_rcp_f32_e32 v218, v218
	v_rcp_f32_e32 v219, v219
	v_mul_f32_e32 v208, v208, v216
	v_mul_f32_e32 v209, v209, v217
	v_mul_f32_e32 v210, v210, v218
	v_mul_f32_e32 v211, v211, v219
	v_mul_f32_e32 v208, v208, v212
	v_mul_f32_e32 v209, v209, v213
	v_mul_f32_e32 v210, v210, v214
	v_mul_f32_e32 v211, v211, v215
	v_cvt_pk_bf16_f32 v172, v208, v209
	v_cvt_pk_bf16_f32 v173, v210, v211
	s_waitcnt lgkmcnt(0)
	v_fma_f32 v208, v120, v100, v128
	v_fma_f32 v209, v121, v101, v129
	v_fma_f32 v210, v122, v102, v130
	v_fma_f32 v211, v123, v103, v131
	v_fmac_f32_dpp v208, v100, v116 row_shr:1 row_mask:0xf bank_mask:0xf
	v_fmac_f32_dpp v209, v101, v117 row_shr:1 row_mask:0xf bank_mask:0xf
	v_fmac_f32_dpp v210, v102, v118 row_shr:1 row_mask:0xf bank_mask:0xf
	v_fmac_f32_dpp v211, v103, v119 row_shr:1 row_mask:0xf bank_mask:0xf
	v_fmac_f32_dpp v208, v100, v124 row_shl:1 row_mask:0xf bank_mask:0xf
	v_fmac_f32_dpp v209, v101, v125 row_shl:1 row_mask:0xf bank_mask:0xf
	v_fmac_f32_dpp v210, v102, v126 row_shl:1 row_mask:0xf bank_mask:0xf
	v_fmac_f32_dpp v211, v103, v127 row_shl:1 row_mask:0xf bank_mask:0xf
	v_fmac_f32_dpp v208, v112, v116 row_shl:15 row_mask:0xf bank_mask:0xf
	v_fmac_f32_dpp v209, v113, v117 row_shl:15 row_mask:0xf bank_mask:0xf
	v_fmac_f32_dpp v210, v114, v118 row_shl:15 row_mask:0xf bank_mask:0xf
	v_fmac_f32_dpp v211, v115, v119 row_shl:15 row_mask:0xf bank_mask:0xf
	v_fmac_f32_dpp v208, v164, v124 row_shr:15 row_mask:0xf bank_mask:0xf
	v_fmac_f32_dpp v209, v165, v125 row_shr:15 row_mask:0xf bank_mask:0xf
	v_fmac_f32_dpp v210, v166, v126 row_shr:15 row_mask:0xf bank_mask:0xf
	v_fmac_f32_dpp v211, v167, v127 row_shr:15 row_mask:0xf bank_mask:0xf
	v_fma_f32 v212, v136, v104, v144
	v_fma_f32 v213, v137, v105, v145
	v_fma_f32 v214, v138, v106, v146
	v_fma_f32 v215, v139, v107, v147
	v_fmac_f32_dpp v212, v104, v132 row_shr:1 row_mask:0xf bank_mask:0xf
	v_fmac_f32_dpp v213, v105, v133 row_shr:1 row_mask:0xf bank_mask:0xf
	v_fmac_f32_dpp v214, v106, v134 row_shr:1 row_mask:0xf bank_mask:0xf
	v_fmac_f32_dpp v215, v107, v135 row_shr:1 row_mask:0xf bank_mask:0xf
	v_fmac_f32_dpp v212, v104, v140 row_shl:1 row_mask:0xf bank_mask:0xf
	v_fmac_f32_dpp v213, v105, v141 row_shl:1 row_mask:0xf bank_mask:0xf
	v_fmac_f32_dpp v214, v106, v142 row_shl:1 row_mask:0xf bank_mask:0xf
	v_fmac_f32_dpp v215, v107, v143 row_shl:1 row_mask:0xf bank_mask:0xf
	v_fmac_f32_dpp v212, v108, v132 row_shl:15 row_mask:0xf bank_mask:0xf
	v_fmac_f32_dpp v213, v109, v133 row_shl:15 row_mask:0xf bank_mask:0xf
	v_fmac_f32_dpp v214, v110, v134 row_shl:15 row_mask:0xf bank_mask:0xf
	v_fmac_f32_dpp v215, v111, v135 row_shl:15 row_mask:0xf bank_mask:0xf
	v_fmac_f32_dpp v212, v168, v140 row_shr:15 row_mask:0xf bank_mask:0xf
	v_fmac_f32_dpp v213, v169, v141 row_shr:15 row_mask:0xf bank_mask:0xf
	v_fmac_f32_dpp v214, v170, v142 row_shr:15 row_mask:0xf bank_mask:0xf
	v_fmac_f32_dpp v215, v171, v143 row_shr:15 row_mask:0xf bank_mask:0xf
	v_mul_f32_e32 v216, 0xbfb8aa3b, v208
	v_mul_f32_e32 v217, 0xbfb8aa3b, v209
	v_mul_f32_e32 v218, 0xbfb8aa3b, v210
	v_mul_f32_e32 v219, 0xbfb8aa3b, v211
	v_exp_f32_e32 v216, v216
	v_exp_f32_e32 v217, v217
	v_exp_f32_e32 v218, v218
	v_exp_f32_e32 v219, v219
	v_add_f32_e32 v216, 1.0, v216
	v_add_f32_e32 v217, 1.0, v217
	v_add_f32_e32 v218, 1.0, v218
	v_add_f32_e32 v219, 1.0, v219
	v_rcp_f32_e32 v216, v216
	v_rcp_f32_e32 v217, v217
	v_rcp_f32_e32 v218, v218
	v_rcp_f32_e32 v219, v219
	v_mul_f32_e32 v208, v208, v216
	v_mul_f32_e32 v209, v209, v217
	v_mul_f32_e32 v210, v210, v218
	v_mul_f32_e32 v211, v211, v219
	v_mul_f32_e32 v208, v208, v212
	v_mul_f32_e32 v209, v209, v213
	v_mul_f32_e32 v210, v210, v214
	v_mul_f32_e32 v211, v211, v215
	v_cvt_pk_bf16_f32 v178, v208, v209
	v_cvt_pk_bf16_f32 v179, v210, v211
	v_readlane_b32 s10, v250, 7
	v_readlane_b32 s11, v250, 8
	v_readlane_b32 s100, v250, 9
	v_readlane_b32 s101, v250, 10
	s_nop 1
	s_add_u32 s12, s10, 0x5800
	s_addc_u32 s13, s11, 0
	s_add_u32 s4, s10, 0xb000
	s_addc_u32 s5, s11, 0
	s_nop 2
	global_load_dwordx4 v[160:163], v245, s[10:11] offset:16
	global_load_dwordx4 v[152:155], v245, s[12:13] offset:16
	global_load_dwordx4 v[112:115], v245, s[4:5] offset:16
	global_load_dwordx4 v[100:103], v245, s[100:101] offset:16
	global_load_dwordx4 v[156:159], v246, s[10:11] offset:16
	global_load_dwordx4 v[148:151], v246, s[12:13] offset:16
	global_load_dwordx4 v[108:111], v246, s[4:5] offset:16
	global_load_dwordx4 v[104:107], v246, s[100:101] offset:16
	ds_read_b128 v[164:167], v221 offset:3072
	ds_read_b128 v[168:171], v221 offset:3584
	v_fma_f32 v208, v120, v88, v128
	v_fma_f32 v209, v121, v89, v129
	v_fma_f32 v210, v122, v90, v130
	v_fma_f32 v211, v123, v91, v131
	v_fmac_f32_dpp v208, v88, v116 row_shr:1 row_mask:0xf bank_mask:0xf
	v_fmac_f32_dpp v209, v89, v117 row_shr:1 row_mask:0xf bank_mask:0xf
	v_fmac_f32_dpp v210, v90, v118 row_shr:1 row_mask:0xf bank_mask:0xf
	v_fmac_f32_dpp v211, v91, v119 row_shr:1 row_mask:0xf bank_mask:0xf
	v_fmac_f32_dpp v208, v88, v124 row_shl:1 row_mask:0xf bank_mask:0xf
	v_fmac_f32_dpp v209, v89, v125 row_shl:1 row_mask:0xf bank_mask:0xf
	v_fmac_f32_dpp v210, v90, v126 row_shl:1 row_mask:0xf bank_mask:0xf
	v_fmac_f32_dpp v211, v91, v127 row_shl:1 row_mask:0xf bank_mask:0xf
	v_fmac_f32_dpp v208, v96, v116 row_shl:15 row_mask:0xf bank_mask:0xf
	v_fmac_f32_dpp v209, v97, v117 row_shl:15 row_mask:0xf bank_mask:0xf
	v_fmac_f32_dpp v210, v98, v118 row_shl:15 row_mask:0xf bank_mask:0xf
	v_fmac_f32_dpp v211, v99, v119 row_shl:15 row_mask:0xf bank_mask:0xf
	v_fmac_f32_dpp v208, v80, v124 row_shr:15 row_mask:0xf bank_mask:0xf
	v_fmac_f32_dpp v209, v81, v125 row_shr:15 row_mask:0xf bank_mask:0xf
	v_fmac_f32_dpp v210, v82, v126 row_shr:15 row_mask:0xf bank_mask:0xf
	v_fmac_f32_dpp v211, v83, v127 row_shr:15 row_mask:0xf bank_mask:0xf
	v_fma_f32 v212, v136, v84, v144
	v_fma_f32 v213, v137, v85, v145
	v_fma_f32 v214, v138, v86, v146
	v_fma_f32 v215, v139, v87, v147
	v_fmac_f32_dpp v212, v84, v132 row_shr:1 row_mask:0xf bank_mask:0xf
	v_fmac_f32_dpp v213, v85, v133 row_shr:1 row_mask:0xf bank_mask:0xf
	v_fmac_f32_dpp v214, v86, v134 row_shr:1 row_mask:0xf bank_mask:0xf
	v_fmac_f32_dpp v215, v87, v135 row_shr:1 row_mask:0xf bank_mask:0xf
	v_fmac_f32_dpp v212, v84, v140 row_shl:1 row_mask:0xf bank_mask:0xf
	v_fmac_f32_dpp v213, v85, v141 row_shl:1 row_mask:0xf bank_mask:0xf
	v_fmac_f32_dpp v214, v86, v142 row_shl:1 row_mask:0xf bank_mask:0xf
	v_fmac_f32_dpp v215, v87, v143 row_shl:1 row_mask:0xf bank_mask:0xf
	v_fmac_f32_dpp v212, v92, v132 row_shl:15 row_mask:0xf bank_mask:0xf
	v_fmac_f32_dpp v213, v93, v133 row_shl:15 row_mask:0xf bank_mask:0xf
	v_fmac_f32_dpp v214, v94, v134 row_shl:15 row_mask:0xf bank_mask:0xf
	v_fmac_f32_dpp v215, v95, v135 row_shl:15 row_mask:0xf bank_mask:0xf
	v_fmac_f32_dpp v212, v76, v140 row_shr:15 row_mask:0xf bank_mask:0xf
	v_fmac_f32_dpp v213, v77, v141 row_shr:15 row_mask:0xf bank_mask:0xf
	v_fmac_f32_dpp v214, v78, v142 row_shr:15 row_mask:0xf bank_mask:0xf
	v_fmac_f32_dpp v215, v79, v143 row_shr:15 row_mask:0xf bank_mask:0xf
	v_mul_f32_e32 v216, 0xbfb8aa3b, v208
	v_mul_f32_e32 v217, 0xbfb8aa3b, v209
	v_mul_f32_e32 v218, 0xbfb8aa3b, v210
	v_mul_f32_e32 v219, 0xbfb8aa3b, v211
	v_exp_f32_e32 v216, v216
	v_exp_f32_e32 v217, v217
	v_exp_f32_e32 v218, v218
	v_exp_f32_e32 v219, v219
	v_add_f32_e32 v216, 1.0, v216
	v_add_f32_e32 v217, 1.0, v217
	v_add_f32_e32 v218, 1.0, v218
	v_add_f32_e32 v219, 1.0, v219
	v_rcp_f32_e32 v216, v216
	v_rcp_f32_e32 v217, v217
	v_rcp_f32_e32 v218, v218
	v_rcp_f32_e32 v219, v219
	v_mul_f32_e32 v208, v208, v216
	v_mul_f32_e32 v209, v209, v217
	v_mul_f32_e32 v210, v210, v218
	v_mul_f32_e32 v211, v211, v219
	v_mul_f32_e32 v208, v208, v212
	v_mul_f32_e32 v209, v209, v213
	v_mul_f32_e32 v210, v210, v214
	v_mul_f32_e32 v211, v211, v215
	v_cvt_pk_bf16_f32 v247, v208, v209
	v_cvt_pk_bf16_f32 v248, v210, v211
	v_fma_f32 v208, v120, v80, v128
	v_fma_f32 v209, v121, v81, v129
	v_fma_f32 v210, v122, v82, v130
	v_fma_f32 v211, v123, v83, v131
	v_fmac_f32_dpp v208, v80, v116 row_shr:1 row_mask:0xf bank_mask:0xf
	v_fmac_f32_dpp v209, v81, v117 row_shr:1 row_mask:0xf bank_mask:0xf
	v_fmac_f32_dpp v210, v82, v118 row_shr:1 row_mask:0xf bank_mask:0xf
	v_fmac_f32_dpp v211, v83, v119 row_shr:1 row_mask:0xf bank_mask:0xf
	v_fmac_f32_dpp v208, v80, v124 row_shl:1 row_mask:0xf bank_mask:0xf
	v_fmac_f32_dpp v209, v81, v125 row_shl:1 row_mask:0xf bank_mask:0xf
	v_fmac_f32_dpp v210, v82, v126 row_shl:1 row_mask:0xf bank_mask:0xf
	v_fmac_f32_dpp v211, v83, v127 row_shl:1 row_mask:0xf bank_mask:0xf
	v_fmac_f32_dpp v208, v88, v116 row_shl:15 row_mask:0xf bank_mask:0xf
	v_fmac_f32_dpp v209, v89, v117 row_shl:15 row_mask:0xf bank_mask:0xf
	v_fmac_f32_dpp v210, v90, v118 row_shl:15 row_mask:0xf bank_mask:0xf
	v_fmac_f32_dpp v211, v91, v119 row_shl:15 row_mask:0xf bank_mask:0xf
	v_fmac_f32_dpp v208, v68, v124 row_shr:15 row_mask:0xf bank_mask:0xf
	v_fmac_f32_dpp v209, v69, v125 row_shr:15 row_mask:0xf bank_mask:0xf
	v_fmac_f32_dpp v210, v70, v126 row_shr:15 row_mask:0xf bank_mask:0xf
	v_fmac_f32_dpp v211, v71, v127 row_shr:15 row_mask:0xf bank_mask:0xf
	v_fma_f32 v212, v136, v76, v144
	v_fma_f32 v213, v137, v77, v145
	v_fma_f32 v214, v138, v78, v146
	v_fma_f32 v215, v139, v79, v147
	v_fmac_f32_dpp v212, v76, v132 row_shr:1 row_mask:0xf bank_mask:0xf
	v_fmac_f32_dpp v213, v77, v133 row_shr:1 row_mask:0xf bank_mask:0xf
	v_fmac_f32_dpp v214, v78, v134 row_shr:1 row_mask:0xf bank_mask:0xf
	v_fmac_f32_dpp v215, v79, v135 row_shr:1 row_mask:0xf bank_mask:0xf
	v_fmac_f32_dpp v212, v76, v140 row_shl:1 row_mask:0xf bank_mask:0xf
	v_fmac_f32_dpp v213, v77, v141 row_shl:1 row_mask:0xf bank_mask:0xf
	v_fmac_f32_dpp v214, v78, v142 row_shl:1 row_mask:0xf bank_mask:0xf
	v_fmac_f32_dpp v215, v79, v143 row_shl:1 row_mask:0xf bank_mask:0xf
	v_fmac_f32_dpp v212, v84, v132 row_shl:15 row_mask:0xf bank_mask:0xf
	v_fmac_f32_dpp v213, v85, v133 row_shl:15 row_mask:0xf bank_mask:0xf
	v_fmac_f32_dpp v214, v86, v134 row_shl:15 row_mask:0xf bank_mask:0xf
	v_fmac_f32_dpp v215, v87, v135 row_shl:15 row_mask:0xf bank_mask:0xf
	v_fmac_f32_dpp v212, v72, v140 row_shr:15 row_mask:0xf bank_mask:0xf
	v_fmac_f32_dpp v213, v73, v141 row_shr:15 row_mask:0xf bank_mask:0xf
	v_fmac_f32_dpp v214, v74, v142 row_shr:15 row_mask:0xf bank_mask:0xf
	v_fmac_f32_dpp v215, v75, v143 row_shr:15 row_mask:0xf bank_mask:0xf
	v_mul_f32_e32 v216, 0xbfb8aa3b, v208
	v_mul_f32_e32 v217, 0xbfb8aa3b, v209
	v_mul_f32_e32 v218, 0xbfb8aa3b, v210
	v_mul_f32_e32 v219, 0xbfb8aa3b, v211
	v_exp_f32_e32 v216, v216
	v_exp_f32_e32 v217, v217
	v_exp_f32_e32 v218, v218
	v_exp_f32_e32 v219, v219
	v_add_f32_e32 v216, 1.0, v216
	v_add_f32_e32 v217, 1.0, v217
	v_add_f32_e32 v218, 1.0, v218
	v_add_f32_e32 v219, 1.0, v219
	v_rcp_f32_e32 v216, v216
	v_rcp_f32_e32 v217, v217
	v_rcp_f32_e32 v218, v218
	v_rcp_f32_e32 v219, v219
	v_mul_f32_e32 v208, v208, v216
	v_mul_f32_e32 v209, v209, v217
	v_mul_f32_e32 v210, v210, v218
	v_mul_f32_e32 v211, v211, v219
	v_mul_f32_e32 v208, v208, v212
	v_mul_f32_e32 v209, v209, v213
	v_mul_f32_e32 v210, v210, v214
	v_mul_f32_e32 v211, v211, v215
	v_cvt_pk_bf16_f32 v249, v208, v209
	v_cvt_pk_bf16_f32 v2, v210, v211
	s_waitcnt lgkmcnt(0)
	v_fma_f32 v208, v120, v96, v128
	v_fma_f32 v209, v121, v97, v129
	v_fma_f32 v210, v122, v98, v130
	v_fma_f32 v211, v123, v99, v131
	v_fmac_f32_dpp v208, v96, v116 row_shr:1 row_mask:0xf bank_mask:0xf
	v_fmac_f32_dpp v209, v97, v117 row_shr:1 row_mask:0xf bank_mask:0xf
	v_fmac_f32_dpp v210, v98, v118 row_shr:1 row_mask:0xf bank_mask:0xf
	v_fmac_f32_dpp v211, v99, v119 row_shr:1 row_mask:0xf bank_mask:0xf
	v_fmac_f32_dpp v208, v96, v124 row_shl:1 row_mask:0xf bank_mask:0xf
	v_fmac_f32_dpp v209, v97, v125 row_shl:1 row_mask:0xf bank_mask:0xf
	v_fmac_f32_dpp v210, v98, v126 row_shl:1 row_mask:0xf bank_mask:0xf
	v_fmac_f32_dpp v211, v99, v127 row_shl:1 row_mask:0xf bank_mask:0xf
	v_fmac_f32_dpp v208, v164, v116 row_shl:15 row_mask:0xf bank_mask:0xf
	v_fmac_f32_dpp v209, v165, v117 row_shl:15 row_mask:0xf bank_mask:0xf
	v_fmac_f32_dpp v210, v166, v118 row_shl:15 row_mask:0xf bank_mask:0xf
	v_fmac_f32_dpp v211, v167, v119 row_shl:15 row_mask:0xf bank_mask:0xf
	v_fmac_f32_dpp v208, v88, v124 row_shr:15 row_mask:0xf bank_mask:0xf
	v_fmac_f32_dpp v209, v89, v125 row_shr:15 row_mask:0xf bank_mask:0xf
	v_fmac_f32_dpp v210, v90, v126 row_shr:15 row_mask:0xf bank_mask:0xf
	v_fmac_f32_dpp v211, v91, v127 row_shr:15 row_mask:0xf bank_mask:0xf
	v_fma_f32 v212, v136, v92, v144
	v_fma_f32 v213, v137, v93, v145
	v_fma_f32 v214, v138, v94, v146
	v_fma_f32 v215, v139, v95, v147
	v_fmac_f32_dpp v212, v92, v132 row_shr:1 row_mask:0xf bank_mask:0xf
	v_fmac_f32_dpp v213, v93, v133 row_shr:1 row_mask:0xf bank_mask:0xf
	v_fmac_f32_dpp v214, v94, v134 row_shr:1 row_mask:0xf bank_mask:0xf
	v_fmac_f32_dpp v215, v95, v135 row_shr:1 row_mask:0xf bank_mask:0xf
	v_fmac_f32_dpp v212, v92, v140 row_shl:1 row_mask:0xf bank_mask:0xf
	v_fmac_f32_dpp v213, v93, v141 row_shl:1 row_mask:0xf bank_mask:0xf
	v_fmac_f32_dpp v214, v94, v142 row_shl:1 row_mask:0xf bank_mask:0xf
	v_fmac_f32_dpp v215, v95, v143 row_shl:1 row_mask:0xf bank_mask:0xf
	v_fmac_f32_dpp v212, v168, v132 row_shl:15 row_mask:0xf bank_mask:0xf
	v_fmac_f32_dpp v213, v169, v133 row_shl:15 row_mask:0xf bank_mask:0xf
	v_fmac_f32_dpp v214, v170, v134 row_shl:15 row_mask:0xf bank_mask:0xf
	v_fmac_f32_dpp v215, v171, v135 row_shl:15 row_mask:0xf bank_mask:0xf
	v_fmac_f32_dpp v212, v84, v140 row_shr:15 row_mask:0xf bank_mask:0xf
	v_fmac_f32_dpp v213, v85, v141 row_shr:15 row_mask:0xf bank_mask:0xf
	v_fmac_f32_dpp v214, v86, v142 row_shr:15 row_mask:0xf bank_mask:0xf
	v_fmac_f32_dpp v215, v87, v143 row_shr:15 row_mask:0xf bank_mask:0xf
	ds_read_b128 v[164:167], v223 offset:0
	ds_read_b128 v[168:171], v223 offset:512
	v_mul_f32_e32 v216, 0xbfb8aa3b, v208
	v_mul_f32_e32 v217, 0xbfb8aa3b, v209
	v_mul_f32_e32 v218, 0xbfb8aa3b, v210
	v_mul_f32_e32 v219, 0xbfb8aa3b, v211
	v_exp_f32_e32 v216, v216
	v_exp_f32_e32 v217, v217
	v_exp_f32_e32 v218, v218
	v_exp_f32_e32 v219, v219
	v_add_f32_e32 v216, 1.0, v216
	v_add_f32_e32 v217, 1.0, v217
	v_add_f32_e32 v218, 1.0, v218
	v_add_f32_e32 v219, 1.0, v219
	v_rcp_f32_e32 v216, v216
	v_rcp_f32_e32 v217, v217
	v_rcp_f32_e32 v218, v218
	v_rcp_f32_e32 v219, v219
	v_mul_f32_e32 v208, v208, v216
	v_mul_f32_e32 v209, v209, v217
	v_mul_f32_e32 v210, v210, v218
	v_mul_f32_e32 v211, v211, v219
	v_mul_f32_e32 v208, v208, v212
	v_mul_f32_e32 v209, v209, v213
	v_mul_f32_e32 v210, v210, v214
	v_mul_f32_e32 v211, v211, v215
	v_cvt_pk_bf16_f32 v242, v208, v209
	v_cvt_pk_bf16_f32 v243, v210, v211
	s_waitcnt lgkmcnt(0)
	v_fma_f32 v208, v120, v68, v128
	v_fma_f32 v209, v121, v69, v129
	v_fma_f32 v210, v122, v70, v130
	v_fma_f32 v211, v123, v71, v131
	v_fmac_f32_dpp v208, v68, v116 row_shr:1 row_mask:0xf bank_mask:0xf
	v_fmac_f32_dpp v209, v69, v117 row_shr:1 row_mask:0xf bank_mask:0xf
	v_fmac_f32_dpp v210, v70, v118 row_shr:1 row_mask:0xf bank_mask:0xf
	v_fmac_f32_dpp v211, v71, v119 row_shr:1 row_mask:0xf bank_mask:0xf
	v_fmac_f32_dpp v208, v68, v124 row_shl:1 row_mask:0xf bank_mask:0xf
	v_fmac_f32_dpp v209, v69, v125 row_shl:1 row_mask:0xf bank_mask:0xf
	v_fmac_f32_dpp v210, v70, v126 row_shl:1 row_mask:0xf bank_mask:0xf
	v_fmac_f32_dpp v211, v71, v127 row_shl:1 row_mask:0xf bank_mask:0xf
	v_fmac_f32_dpp v208, v80, v116 row_shl:15 row_mask:0xf bank_mask:0xf
	v_fmac_f32_dpp v209, v81, v117 row_shl:15 row_mask:0xf bank_mask:0xf
	v_fmac_f32_dpp v210, v82, v118 row_shl:15 row_mask:0xf bank_mask:0xf
	v_fmac_f32_dpp v211, v83, v119 row_shl:15 row_mask:0xf bank_mask:0xf
	v_fmac_f32_dpp v208, v164, v124 row_shr:15 row_mask:0xf bank_mask:0xf
	v_fmac_f32_dpp v209, v165, v125 row_shr:15 row_mask:0xf bank_mask:0xf
	v_fmac_f32_dpp v210, v166, v126 row_shr:15 row_mask:0xf bank_mask:0xf
	v_fmac_f32_dpp v211, v167, v127 row_shr:15 row_mask:0xf bank_mask:0xf
	v_fma_f32 v212, v136, v72, v144
	v_fma_f32 v213, v137, v73, v145
	v_fma_f32 v214, v138, v74, v146
	v_fma_f32 v215, v139, v75, v147
	v_fmac_f32_dpp v212, v72, v132 row_shr:1 row_mask:0xf bank_mask:0xf
	v_fmac_f32_dpp v213, v73, v133 row_shr:1 row_mask:0xf bank_mask:0xf
	v_fmac_f32_dpp v214, v74, v134 row_shr:1 row_mask:0xf bank_mask:0xf
	v_fmac_f32_dpp v215, v75, v135 row_shr:1 row_mask:0xf bank_mask:0xf
	v_fmac_f32_dpp v212, v72, v140 row_shl:1 row_mask:0xf bank_mask:0xf
	v_fmac_f32_dpp v213, v73, v141 row_shl:1 row_mask:0xf bank_mask:0xf
	v_fmac_f32_dpp v214, v74, v142 row_shl:1 row_mask:0xf bank_mask:0xf
	v_fmac_f32_dpp v215, v75, v143 row_shl:1 row_mask:0xf bank_mask:0xf
	v_fmac_f32_dpp v212, v76, v132 row_shl:15 row_mask:0xf bank_mask:0xf
	v_fmac_f32_dpp v213, v77, v133 row_shl:15 row_mask:0xf bank_mask:0xf
	v_fmac_f32_dpp v214, v78, v134 row_shl:15 row_mask:0xf bank_mask:0xf
	v_fmac_f32_dpp v215, v79, v135 row_shl:15 row_mask:0xf bank_mask:0xf
	v_fmac_f32_dpp v212, v168, v140 row_shr:15 row_mask:0xf bank_mask:0xf
	v_fmac_f32_dpp v213, v169, v141 row_shr:15 row_mask:0xf bank_mask:0xf
	v_fmac_f32_dpp v214, v170, v142 row_shr:15 row_mask:0xf bank_mask:0xf
	v_fmac_f32_dpp v215, v171, v143 row_shr:15 row_mask:0xf bank_mask:0xf
	v_mul_f32_e32 v216, 0xbfb8aa3b, v208
	v_mul_f32_e32 v217, 0xbfb8aa3b, v209
	v_mul_f32_e32 v218, 0xbfb8aa3b, v210
	v_mul_f32_e32 v219, 0xbfb8aa3b, v211
	v_exp_f32_e32 v216, v216
	v_exp_f32_e32 v217, v217
	v_exp_f32_e32 v218, v218
	v_exp_f32_e32 v219, v219
	v_add_f32_e32 v216, 1.0, v216
	v_add_f32_e32 v217, 1.0, v217
	v_add_f32_e32 v218, 1.0, v218
	v_add_f32_e32 v219, 1.0, v219
	v_rcp_f32_e32 v216, v216
	v_rcp_f32_e32 v217, v217
	v_rcp_f32_e32 v218, v218
	v_rcp_f32_e32 v219, v219
	v_mul_f32_e32 v208, v208, v216
	v_mul_f32_e32 v209, v209, v217
	v_mul_f32_e32 v210, v210, v218
	v_mul_f32_e32 v211, v211, v219
	v_mul_f32_e32 v208, v208, v212
	v_mul_f32_e32 v209, v209, v213
	v_mul_f32_e32 v210, v210, v214
	v_mul_f32_e32 v211, v211, v215
	v_cvt_pk_bf16_f32 v206, v208, v209
	v_cvt_pk_bf16_f32 v207, v210, v211
	ds_read_b128 v[164:167], v222 offset:16
	ds_read_b128 v[168:171], v222 offset:528
	s_waitcnt vmcnt(0)
	v_fma_f32 v208, v152, v56, v100
	v_fma_f32 v209, v153, v57, v101
	v_fma_f32 v210, v154, v58, v102
	v_fma_f32 v211, v155, v59, v103
	v_fmac_f32_dpp v208, v56, v160 row_shr:1 row_mask:0xf bank_mask:0xf
	v_fmac_f32_dpp v209, v57, v161 row_shr:1 row_mask:0xf bank_mask:0xf
	v_fmac_f32_dpp v210, v58, v162 row_shr:1 row_mask:0xf bank_mask:0xf
	v_fmac_f32_dpp v211, v59, v163 row_shr:1 row_mask:0xf bank_mask:0xf
	v_fmac_f32_dpp v208, v56, v112 row_shl:1 row_mask:0xf bank_mask:0xf
	v_fmac_f32_dpp v209, v57, v113 row_shl:1 row_mask:0xf bank_mask:0xf
	v_fmac_f32_dpp v210, v58, v114 row_shl:1 row_mask:0xf bank_mask:0xf
	v_fmac_f32_dpp v211, v59, v115 row_shl:1 row_mask:0xf bank_mask:0xf
	v_fmac_f32_dpp v208, v64, v160 row_shl:15 row_mask:0xf bank_mask:0xf
	v_fmac_f32_dpp v209, v65, v161 row_shl:15 row_mask:0xf bank_mask:0xf
	v_fmac_f32_dpp v210, v66, v162 row_shl:15 row_mask:0xf bank_mask:0xf
	v_fmac_f32_dpp v211, v67, v163 row_shl:15 row_mask:0xf bank_mask:0xf
	v_fmac_f32_dpp v208, v48, v112 row_shr:15 row_mask:0xf bank_mask:0xf
	v_fmac_f32_dpp v209, v49, v113 row_shr:15 row_mask:0xf bank_mask:0xf
	v_fmac_f32_dpp v210, v50, v114 row_shr:15 row_mask:0xf bank_mask:0xf
	v_fmac_f32_dpp v211, v51, v115 row_shr:15 row_mask:0xf bank_mask:0xf
	v_fma_f32 v212, v148, v52, v104
	v_fma_f32 v213, v149, v53, v105
	v_fma_f32 v214, v150, v54, v106
	v_fma_f32 v215, v151, v55, v107
	v_fmac_f32_dpp v212, v52, v156 row_shr:1 row_mask:0xf bank_mask:0xf
	v_fmac_f32_dpp v213, v53, v157 row_shr:1 row_mask:0xf bank_mask:0xf
	v_fmac_f32_dpp v214, v54, v158 row_shr:1 row_mask:0xf bank_mask:0xf
	v_fmac_f32_dpp v215, v55, v159 row_shr:1 row_mask:0xf bank_mask:0xf
	v_fmac_f32_dpp v212, v52, v108 row_shl:1 row_mask:0xf bank_mask:0xf
	v_fmac_f32_dpp v213, v53, v109 row_shl:1 row_mask:0xf bank_mask:0xf
	v_fmac_f32_dpp v214, v54, v110 row_shl:1 row_mask:0xf bank_mask:0xf
	v_fmac_f32_dpp v215, v55, v111 row_shl:1 row_mask:0xf bank_mask:0xf
	v_fmac_f32_dpp v212, v60, v156 row_shl:15 row_mask:0xf bank_mask:0xf
	v_fmac_f32_dpp v213, v61, v157 row_shl:15 row_mask:0xf bank_mask:0xf
	v_fmac_f32_dpp v214, v62, v158 row_shl:15 row_mask:0xf bank_mask:0xf
	v_fmac_f32_dpp v215, v63, v159 row_shl:15 row_mask:0xf bank_mask:0xf
	v_fmac_f32_dpp v212, v44, v108 row_shr:15 row_mask:0xf bank_mask:0xf
	v_fmac_f32_dpp v213, v45, v109 row_shr:15 row_mask:0xf bank_mask:0xf
	v_fmac_f32_dpp v214, v46, v110 row_shr:15 row_mask:0xf bank_mask:0xf
	v_fmac_f32_dpp v215, v47, v111 row_shr:15 row_mask:0xf bank_mask:0xf
	v_mul_f32_e32 v216, 0xbfb8aa3b, v208
	v_mul_f32_e32 v217, 0xbfb8aa3b, v209
	v_mul_f32_e32 v218, 0xbfb8aa3b, v210
	v_mul_f32_e32 v219, 0xbfb8aa3b, v211
	v_exp_f32_e32 v216, v216
	v_exp_f32_e32 v217, v217
	v_exp_f32_e32 v218, v218
	v_exp_f32_e32 v219, v219
	v_add_f32_e32 v216, 1.0, v216
	v_add_f32_e32 v217, 1.0, v217
	v_add_f32_e32 v218, 1.0, v218
	v_add_f32_e32 v219, 1.0, v219
	v_rcp_f32_e32 v216, v216
	v_rcp_f32_e32 v217, v217
	v_rcp_f32_e32 v218, v218
	v_rcp_f32_e32 v219, v219
	v_mul_f32_e32 v208, v208, v216
	v_mul_f32_e32 v209, v209, v217
	v_mul_f32_e32 v210, v210, v218
	v_mul_f32_e32 v211, v211, v219
	v_mul_f32_e32 v208, v208, v212
	v_mul_f32_e32 v209, v209, v213
	v_mul_f32_e32 v210, v210, v214
	v_mul_f32_e32 v211, v211, v215
	v_cvt_pk_bf16_f32 v118, v208, v209
	v_cvt_pk_bf16_f32 v119, v210, v211
	v_mov_b32_e32 v116, v174
	v_mov_b32_e32 v117, v175
	s_add_u32 s4, s6, 0x16000
	s_addc_u32 s5, s7, 0
	global_store_dwordx4 v244, v[116:119], s[4:5] sc1
	v_fma_f32 v208, v152, v48, v100
	v_fma_f32 v209, v153, v49, v101
	v_fma_f32 v210, v154, v50, v102
	v_fma_f32 v211, v155, v51, v103
	v_fmac_f32_dpp v208, v48, v160 row_shr:1 row_mask:0xf bank_mask:0xf
	v_fmac_f32_dpp v209, v49, v161 row_shr:1 row_mask:0xf bank_mask:0xf
	v_fmac_f32_dpp v210, v50, v162 row_shr:1 row_mask:0xf bank_mask:0xf
	v_fmac_f32_dpp v211, v51, v163 row_shr:1 row_mask:0xf bank_mask:0xf
	v_fmac_f32_dpp v208, v48, v112 row_shl:1 row_mask:0xf bank_mask:0xf
	v_fmac_f32_dpp v209, v49, v113 row_shl:1 row_mask:0xf bank_mask:0xf
	v_fmac_f32_dpp v210, v50, v114 row_shl:1 row_mask:0xf bank_mask:0xf
	v_fmac_f32_dpp v211, v51, v115 row_shl:1 row_mask:0xf bank_mask:0xf
	v_fmac_f32_dpp v208, v56, v160 row_shl:15 row_mask:0xf bank_mask:0xf
	v_fmac_f32_dpp v209, v57, v161 row_shl:15 row_mask:0xf bank_mask:0xf
	v_fmac_f32_dpp v210, v58, v162 row_shl:15 row_mask:0xf bank_mask:0xf
	v_fmac_f32_dpp v211, v59, v163 row_shl:15 row_mask:0xf bank_mask:0xf
	v_fmac_f32_dpp v208, v36, v112 row_shr:15 row_mask:0xf bank_mask:0xf
	v_fmac_f32_dpp v209, v37, v113 row_shr:15 row_mask:0xf bank_mask:0xf
	v_fmac_f32_dpp v210, v38, v114 row_shr:15 row_mask:0xf bank_mask:0xf
	v_fmac_f32_dpp v211, v39, v115 row_shr:15 row_mask:0xf bank_mask:0xf
	v_fma_f32 v212, v148, v44, v104
	v_fma_f32 v213, v149, v45, v105
	v_fma_f32 v214, v150, v46, v106
	v_fma_f32 v215, v151, v47, v107
	v_fmac_f32_dpp v212, v44, v156 row_shr:1 row_mask:0xf bank_mask:0xf
	v_fmac_f32_dpp v213, v45, v157 row_shr:1 row_mask:0xf bank_mask:0xf
	v_fmac_f32_dpp v214, v46, v158 row_shr:1 row_mask:0xf bank_mask:0xf
	v_fmac_f32_dpp v215, v47, v159 row_shr:1 row_mask:0xf bank_mask:0xf
	v_fmac_f32_dpp v212, v44, v108 row_shl:1 row_mask:0xf bank_mask:0xf
	v_fmac_f32_dpp v213, v45, v109 row_shl:1 row_mask:0xf bank_mask:0xf
	v_fmac_f32_dpp v214, v46, v110 row_shl:1 row_mask:0xf bank_mask:0xf
	v_fmac_f32_dpp v215, v47, v111 row_shl:1 row_mask:0xf bank_mask:0xf
	v_fmac_f32_dpp v212, v52, v156 row_shl:15 row_mask:0xf bank_mask:0xf
	v_fmac_f32_dpp v213, v53, v157 row_shl:15 row_mask:0xf bank_mask:0xf
	v_fmac_f32_dpp v214, v54, v158 row_shl:15 row_mask:0xf bank_mask:0xf
	v_fmac_f32_dpp v215, v55, v159 row_shl:15 row_mask:0xf bank_mask:0xf
	v_fmac_f32_dpp v212, v40, v108 row_shr:15 row_mask:0xf bank_mask:0xf
	v_fmac_f32_dpp v213, v41, v109 row_shr:15 row_mask:0xf bank_mask:0xf
	v_fmac_f32_dpp v214, v42, v110 row_shr:15 row_mask:0xf bank_mask:0xf
	v_fmac_f32_dpp v215, v43, v111 row_shr:15 row_mask:0xf bank_mask:0xf
	v_mul_f32_e32 v216, 0xbfb8aa3b, v208
	v_mul_f32_e32 v217, 0xbfb8aa3b, v209
	v_mul_f32_e32 v218, 0xbfb8aa3b, v210
	v_mul_f32_e32 v219, 0xbfb8aa3b, v211
	v_exp_f32_e32 v216, v216
	v_exp_f32_e32 v217, v217
	v_exp_f32_e32 v218, v218
	v_exp_f32_e32 v219, v219
	v_add_f32_e32 v216, 1.0, v216
	v_add_f32_e32 v217, 1.0, v217
	v_add_f32_e32 v218, 1.0, v218
	v_add_f32_e32 v219, 1.0, v219
	v_rcp_f32_e32 v216, v216
	v_rcp_f32_e32 v217, v217
	v_rcp_f32_e32 v218, v218
	v_rcp_f32_e32 v219, v219
	v_mul_f32_e32 v208, v208, v216
	v_mul_f32_e32 v209, v209, v217
	v_mul_f32_e32 v210, v210, v218
	v_mul_f32_e32 v211, v211, v219
	v_mul_f32_e32 v208, v208, v212
	v_mul_f32_e32 v209, v209, v213
	v_mul_f32_e32 v210, v210, v214
	v_mul_f32_e32 v211, v211, v215
	v_cvt_pk_bf16_f32 v122, v208, v209
	v_cvt_pk_bf16_f32 v123, v210, v211
	v_mov_b32_e32 v120, v176
	v_mov_b32_e32 v121, v177
	s_add_u32 s4, s6, 0x2c000
	s_addc_u32 s5, s7, 0
	global_store_dwordx4 v244, v[120:123], s[4:5] sc1
	s_waitcnt lgkmcnt(0)
	v_fma_f32 v208, v152, v64, v100
	v_fma_f32 v209, v153, v65, v101
	v_fma_f32 v210, v154, v66, v102
	v_fma_f32 v211, v155, v67, v103
	v_fmac_f32_dpp v208, v64, v160 row_shr:1 row_mask:0xf bank_mask:0xf
	v_fmac_f32_dpp v209, v65, v161 row_shr:1 row_mask:0xf bank_mask:0xf
	v_fmac_f32_dpp v210, v66, v162 row_shr:1 row_mask:0xf bank_mask:0xf
	v_fmac_f32_dpp v211, v67, v163 row_shr:1 row_mask:0xf bank_mask:0xf
	v_fmac_f32_dpp v208, v64, v112 row_shl:1 row_mask:0xf bank_mask:0xf
	v_fmac_f32_dpp v209, v65, v113 row_shl:1 row_mask:0xf bank_mask:0xf
	v_fmac_f32_dpp v210, v66, v114 row_shl:1 row_mask:0xf bank_mask:0xf
	v_fmac_f32_dpp v211, v67, v115 row_shl:1 row_mask:0xf bank_mask:0xf
	v_fmac_f32_dpp v208, v164, v160 row_shl:15 row_mask:0xf bank_mask:0xf
	v_fmac_f32_dpp v209, v165, v161 row_shl:15 row_mask:0xf bank_mask:0xf
	v_fmac_f32_dpp v210, v166, v162 row_shl:15 row_mask:0xf bank_mask:0xf
	v_fmac_f32_dpp v211, v167, v163 row_shl:15 row_mask:0xf bank_mask:0xf
	v_fmac_f32_dpp v208, v56, v112 row_shr:15 row_mask:0xf bank_mask:0xf
	v_fmac_f32_dpp v209, v57, v113 row_shr:15 row_mask:0xf bank_mask:0xf
	v_fmac_f32_dpp v210, v58, v114 row_shr:15 row_mask:0xf bank_mask:0xf
	v_fmac_f32_dpp v211, v59, v115 row_shr:15 row_mask:0xf bank_mask:0xf
	v_fma_f32 v212, v148, v60, v104
	v_fma_f32 v213, v149, v61, v105
	v_fma_f32 v214, v150, v62, v106
	v_fma_f32 v215, v151, v63, v107
	v_fmac_f32_dpp v212, v60, v156 row_shr:1 row_mask:0xf bank_mask:0xf
	v_fmac_f32_dpp v213, v61, v157 row_shr:1 row_mask:0xf bank_mask:0xf
	v_fmac_f32_dpp v214, v62, v158 row_shr:1 row_mask:0xf bank_mask:0xf
	v_fmac_f32_dpp v215, v63, v159 row_shr:1 row_mask:0xf bank_mask:0xf
	v_fmac_f32_dpp v212, v60, v108 row_shl:1 row_mask:0xf bank_mask:0xf
	v_fmac_f32_dpp v213, v61, v109 row_shl:1 row_mask:0xf bank_mask:0xf
	v_fmac_f32_dpp v214, v62, v110 row_shl:1 row_mask:0xf bank_mask:0xf
	v_fmac_f32_dpp v215, v63, v111 row_shl:1 row_mask:0xf bank_mask:0xf
	v_fmac_f32_dpp v212, v168, v156 row_shl:15 row_mask:0xf bank_mask:0xf
	v_fmac_f32_dpp v213, v169, v157 row_shl:15 row_mask:0xf bank_mask:0xf
	v_fmac_f32_dpp v214, v170, v158 row_shl:15 row_mask:0xf bank_mask:0xf
	v_fmac_f32_dpp v215, v171, v159 row_shl:15 row_mask:0xf bank_mask:0xf
	v_fmac_f32_dpp v212, v52, v108 row_shr:15 row_mask:0xf bank_mask:0xf
	v_fmac_f32_dpp v213, v53, v109 row_shr:15 row_mask:0xf bank_mask:0xf
	v_fmac_f32_dpp v214, v54, v110 row_shr:15 row_mask:0xf bank_mask:0xf
	v_fmac_f32_dpp v215, v55, v111 row_shr:15 row_mask:0xf bank_mask:0xf
	ds_read_b128 v[164:167], v221 offset:2064
	ds_read_b128 v[168:171], v221 offset:2576
	v_mul_f32_e32 v216, 0xbfb8aa3b, v208
	v_mul_f32_e32 v217, 0xbfb8aa3b, v209
	v_mul_f32_e32 v218, 0xbfb8aa3b, v210
	v_mul_f32_e32 v219, 0xbfb8aa3b, v211
	v_exp_f32_e32 v216, v216
	v_exp_f32_e32 v217, v217
	v_exp_f32_e32 v218, v218
	v_exp_f32_e32 v219, v219
	v_add_f32_e32 v216, 1.0, v216
	v_add_f32_e32 v217, 1.0, v217
	v_add_f32_e32 v218, 1.0, v218
	v_add_f32_e32 v219, 1.0, v219
	v_rcp_f32_e32 v216, v216
	v_rcp_f32_e32 v217, v217
	v_rcp_f32_e32 v218, v218
	v_rcp_f32_e32 v219, v219
	v_mul_f32_e32 v208, v208, v216
	v_mul_f32_e32 v209, v209, v217
	v_mul_f32_e32 v210, v210, v218
	v_mul_f32_e32 v211, v211, v219
	v_mul_f32_e32 v208, v208, v212
	v_mul_f32_e32 v209, v209, v213
	v_mul_f32_e32 v210, v210, v214
	v_mul_f32_e32 v211, v211, v215
	v_cvt_pk_bf16_f32 v118, v208, v209
	v_cvt_pk_bf16_f32 v119, v210, v211
	v_mov_b32_e32 v116, v172
	v_mov_b32_e32 v117, v173
	s_cmp_eq_u32 s98, 0
	s_cselect_b32 s99, 0xfffefffe, -1
	s_mov_b32 exec_lo, s99
	s_mov_b32 exec_hi, s99
	global_store_dwordx4 v244, v[116:119], s[6:7] sc1
	s_mov_b64 exec, -1
	s_waitcnt lgkmcnt(0)
	v_fma_f32 v208, v152, v36, v100
	v_fma_f32 v209, v153, v37, v101
	v_fma_f32 v210, v154, v38, v102
	v_fma_f32 v211, v155, v39, v103
	v_fmac_f32_dpp v208, v36, v160 row_shr:1 row_mask:0xf bank_mask:0xf
	v_fmac_f32_dpp v209, v37, v161 row_shr:1 row_mask:0xf bank_mask:0xf
	v_fmac_f32_dpp v210, v38, v162 row_shr:1 row_mask:0xf bank_mask:0xf
	v_fmac_f32_dpp v211, v39, v163 row_shr:1 row_mask:0xf bank_mask:0xf
	v_fmac_f32_dpp v208, v36, v112 row_shl:1 row_mask:0xf bank_mask:0xf
	v_fmac_f32_dpp v209, v37, v113 row_shl:1 row_mask:0xf bank_mask:0xf
	v_fmac_f32_dpp v210, v38, v114 row_shl:1 row_mask:0xf bank_mask:0xf
	v_fmac_f32_dpp v211, v39, v115 row_shl:1 row_mask:0xf bank_mask:0xf
	v_fmac_f32_dpp v208, v48, v160 row_shl:15 row_mask:0xf bank_mask:0xf
	v_fmac_f32_dpp v209, v49, v161 row_shl:15 row_mask:0xf bank_mask:0xf
	v_fmac_f32_dpp v210, v50, v162 row_shl:15 row_mask:0xf bank_mask:0xf
	v_fmac_f32_dpp v211, v51, v163 row_shl:15 row_mask:0xf bank_mask:0xf
	v_fmac_f32_dpp v208, v164, v112 row_shr:15 row_mask:0xf bank_mask:0xf
	v_fmac_f32_dpp v209, v165, v113 row_shr:15 row_mask:0xf bank_mask:0xf
	v_fmac_f32_dpp v210, v166, v114 row_shr:15 row_mask:0xf bank_mask:0xf
	v_fmac_f32_dpp v211, v167, v115 row_shr:15 row_mask:0xf bank_mask:0xf
	v_fma_f32 v212, v148, v40, v104
	v_fma_f32 v213, v149, v41, v105
	v_fma_f32 v214, v150, v42, v106
	v_fma_f32 v215, v151, v43, v107
	v_fmac_f32_dpp v212, v40, v156 row_shr:1 row_mask:0xf bank_mask:0xf
	v_fmac_f32_dpp v213, v41, v157 row_shr:1 row_mask:0xf bank_mask:0xf
	v_fmac_f32_dpp v214, v42, v158 row_shr:1 row_mask:0xf bank_mask:0xf
	v_fmac_f32_dpp v215, v43, v159 row_shr:1 row_mask:0xf bank_mask:0xf
	v_fmac_f32_dpp v212, v40, v108 row_shl:1 row_mask:0xf bank_mask:0xf
	v_fmac_f32_dpp v213, v41, v109 row_shl:1 row_mask:0xf bank_mask:0xf
	v_fmac_f32_dpp v214, v42, v110 row_shl:1 row_mask:0xf bank_mask:0xf
	v_fmac_f32_dpp v215, v43, v111 row_shl:1 row_mask:0xf bank_mask:0xf
	v_fmac_f32_dpp v212, v44, v156 row_shl:15 row_mask:0xf bank_mask:0xf
	v_fmac_f32_dpp v213, v45, v157 row_shl:15 row_mask:0xf bank_mask:0xf
	v_fmac_f32_dpp v214, v46, v158 row_shl:15 row_mask:0xf bank_mask:0xf
	v_fmac_f32_dpp v215, v47, v159 row_shl:15 row_mask:0xf bank_mask:0xf
	v_fmac_f32_dpp v212, v168, v108 row_shr:15 row_mask:0xf bank_mask:0xf
	v_fmac_f32_dpp v213, v169, v109 row_shr:15 row_mask:0xf bank_mask:0xf
	v_fmac_f32_dpp v214, v170, v110 row_shr:15 row_mask:0xf bank_mask:0xf
	v_fmac_f32_dpp v215, v171, v111 row_shr:15 row_mask:0xf bank_mask:0xf
	v_mul_f32_e32 v216, 0xbfb8aa3b, v208
	v_mul_f32_e32 v217, 0xbfb8aa3b, v209
	v_mul_f32_e32 v218, 0xbfb8aa3b, v210
	v_mul_f32_e32 v219, 0xbfb8aa3b, v211
	v_exp_f32_e32 v216, v216
	v_exp_f32_e32 v217, v217
	v_exp_f32_e32 v218, v218
	v_exp_f32_e32 v219, v219
	v_add_f32_e32 v216, 1.0, v216
	v_add_f32_e32 v217, 1.0, v217
	v_add_f32_e32 v218, 1.0, v218
	v_add_f32_e32 v219, 1.0, v219
	v_rcp_f32_e32 v216, v216
	v_rcp_f32_e32 v217, v217
	v_rcp_f32_e32 v218, v218
	v_rcp_f32_e32 v219, v219
	v_mul_f32_e32 v208, v208, v216
	v_mul_f32_e32 v209, v209, v217
	v_mul_f32_e32 v210, v210, v218
	v_mul_f32_e32 v211, v211, v219
	v_mul_f32_e32 v208, v208, v212
	v_mul_f32_e32 v209, v209, v213
	v_mul_f32_e32 v210, v210, v214
	v_mul_f32_e32 v211, v211, v215
	v_cvt_pk_bf16_f32 v122, v208, v209
	v_cvt_pk_bf16_f32 v123, v210, v211
	v_mov_b32_e32 v120, v178
	v_mov_b32_e32 v121, v179
	s_add_u32 s4, s6, 0x42000
	s_addc_u32 s5, s7, 0
	global_store_dwordx4 v244, v[120:123], s[4:5] sc1
	ds_read_b128 v[164:167], v221 offset:3088
	ds_read_b128 v[168:171], v221 offset:3600
	v_fma_f32 v208, v152, v24, v100
	v_fma_f32 v209, v153, v25, v101
	v_fma_f32 v210, v154, v26, v102
	v_fma_f32 v211, v155, v27, v103
	v_fmac_f32_dpp v208, v24, v160 row_shr:1 row_mask:0xf bank_mask:0xf
	v_fmac_f32_dpp v209, v25, v161 row_shr:1 row_mask:0xf bank_mask:0xf
	v_fmac_f32_dpp v210, v26, v162 row_shr:1 row_mask:0xf bank_mask:0xf
	v_fmac_f32_dpp v211, v27, v163 row_shr:1 row_mask:0xf bank_mask:0xf
	v_fmac_f32_dpp v208, v24, v112 row_shl:1 row_mask:0xf bank_mask:0xf
	v_fmac_f32_dpp v209, v25, v113 row_shl:1 row_mask:0xf bank_mask:0xf
	v_fmac_f32_dpp v210, v26, v114 row_shl:1 row_mask:0xf bank_mask:0xf
	v_fmac_f32_dpp v211, v27, v115 row_shl:1 row_mask:0xf bank_mask:0xf
	v_fmac_f32_dpp v208, v32, v160 row_shl:15 row_mask:0xf bank_mask:0xf
	v_fmac_f32_dpp v209, v33, v161 row_shl:15 row_mask:0xf bank_mask:0xf
	v_fmac_f32_dpp v210, v34, v162 row_shl:15 row_mask:0xf bank_mask:0xf
	v_fmac_f32_dpp v211, v35, v163 row_shl:15 row_mask:0xf bank_mask:0xf
	v_fmac_f32_dpp v208, v16, v112 row_shr:15 row_mask:0xf bank_mask:0xf
	v_fmac_f32_dpp v209, v17, v113 row_shr:15 row_mask:0xf bank_mask:0xf
	v_fmac_f32_dpp v210, v18, v114 row_shr:15 row_mask:0xf bank_mask:0xf
	v_fmac_f32_dpp v211, v19, v115 row_shr:15 row_mask:0xf bank_mask:0xf
	v_fma_f32 v212, v148, v20, v104
	v_fma_f32 v213, v149, v21, v105
	v_fma_f32 v214, v150, v22, v106
	v_fma_f32 v215, v151, v23, v107
	v_fmac_f32_dpp v212, v20, v156 row_shr:1 row_mask:0xf bank_mask:0xf
	v_fmac_f32_dpp v213, v21, v157 row_shr:1 row_mask:0xf bank_mask:0xf
	v_fmac_f32_dpp v214, v22, v158 row_shr:1 row_mask:0xf bank_mask:0xf
	v_fmac_f32_dpp v215, v23, v159 row_shr:1 row_mask:0xf bank_mask:0xf
	v_fmac_f32_dpp v212, v20, v108 row_shl:1 row_mask:0xf bank_mask:0xf
	v_fmac_f32_dpp v213, v21, v109 row_shl:1 row_mask:0xf bank_mask:0xf
	v_fmac_f32_dpp v214, v22, v110 row_shl:1 row_mask:0xf bank_mask:0xf
	v_fmac_f32_dpp v215, v23, v111 row_shl:1 row_mask:0xf bank_mask:0xf
	v_fmac_f32_dpp v212, v28, v156 row_shl:15 row_mask:0xf bank_mask:0xf
	v_fmac_f32_dpp v213, v29, v157 row_shl:15 row_mask:0xf bank_mask:0xf
	v_fmac_f32_dpp v214, v30, v158 row_shl:15 row_mask:0xf bank_mask:0xf
	v_fmac_f32_dpp v215, v31, v159 row_shl:15 row_mask:0xf bank_mask:0xf
	v_fmac_f32_dpp v212, v12, v108 row_shr:15 row_mask:0xf bank_mask:0xf
	v_fmac_f32_dpp v213, v13, v109 row_shr:15 row_mask:0xf bank_mask:0xf
	v_fmac_f32_dpp v214, v14, v110 row_shr:15 row_mask:0xf bank_mask:0xf
	v_fmac_f32_dpp v215, v15, v111 row_shr:15 row_mask:0xf bank_mask:0xf
	v_mul_f32_e32 v216, 0xbfb8aa3b, v208
	v_mul_f32_e32 v217, 0xbfb8aa3b, v209
	v_mul_f32_e32 v218, 0xbfb8aa3b, v210
	v_mul_f32_e32 v219, 0xbfb8aa3b, v211
	v_exp_f32_e32 v216, v216
	v_exp_f32_e32 v217, v217
	v_exp_f32_e32 v218, v218
	v_exp_f32_e32 v219, v219
	v_add_f32_e32 v216, 1.0, v216
	v_add_f32_e32 v217, 1.0, v217
	v_add_f32_e32 v218, 1.0, v218
	v_add_f32_e32 v219, 1.0, v219
	v_rcp_f32_e32 v216, v216
	v_rcp_f32_e32 v217, v217
	v_rcp_f32_e32 v218, v218
	v_rcp_f32_e32 v219, v219
	v_mul_f32_e32 v208, v208, v216
	v_mul_f32_e32 v209, v209, v217
	v_mul_f32_e32 v210, v210, v218
	v_mul_f32_e32 v211, v211, v219
	v_mul_f32_e32 v208, v208, v212
	v_mul_f32_e32 v209, v209, v213
	v_mul_f32_e32 v210, v210, v214
	v_mul_f32_e32 v211, v211, v215
	v_cvt_pk_bf16_f32 v118, v208, v209
	v_cvt_pk_bf16_f32 v119, v210, v211
	v_mov_b32_e32 v116, v247
	v_mov_b32_e32 v117, v248
	s_add_u32 s4, s6, 0xc6000
	s_addc_u32 s5, s7, 0
	global_store_dwordx4 v244, v[116:119], s[4:5] sc1
	v_fma_f32 v208, v152, v16, v100
	v_fma_f32 v209, v153, v17, v101
	v_fma_f32 v210, v154, v18, v102
	v_fma_f32 v211, v155, v19, v103
	v_fmac_f32_dpp v208, v16, v160 row_shr:1 row_mask:0xf bank_mask:0xf
	v_fmac_f32_dpp v209, v17, v161 row_shr:1 row_mask:0xf bank_mask:0xf
	v_fmac_f32_dpp v210, v18, v162 row_shr:1 row_mask:0xf bank_mask:0xf
	v_fmac_f32_dpp v211, v19, v163 row_shr:1 row_mask:0xf bank_mask:0xf
	v_fmac_f32_dpp v208, v16, v112 row_shl:1 row_mask:0xf bank_mask:0xf
	v_fmac_f32_dpp v209, v17, v113 row_shl:1 row_mask:0xf bank_mask:0xf
	v_fmac_f32_dpp v210, v18, v114 row_shl:1 row_mask:0xf bank_mask:0xf
	v_fmac_f32_dpp v211, v19, v115 row_shl:1 row_mask:0xf bank_mask:0xf
	v_fmac_f32_dpp v208, v24, v160 row_shl:15 row_mask:0xf bank_mask:0xf
	v_fmac_f32_dpp v209, v25, v161 row_shl:15 row_mask:0xf bank_mask:0xf
	v_fmac_f32_dpp v210, v26, v162 row_shl:15 row_mask:0xf bank_mask:0xf
	v_fmac_f32_dpp v211, v27, v163 row_shl:15 row_mask:0xf bank_mask:0xf
	v_fmac_f32_dpp v208, v4, v112 row_shr:15 row_mask:0xf bank_mask:0xf
	v_fmac_f32_dpp v209, v5, v113 row_shr:15 row_mask:0xf bank_mask:0xf
	v_fmac_f32_dpp v210, v6, v114 row_shr:15 row_mask:0xf bank_mask:0xf
	v_fmac_f32_dpp v211, v7, v115 row_shr:15 row_mask:0xf bank_mask:0xf
	v_fma_f32 v212, v148, v12, v104
	v_fma_f32 v213, v149, v13, v105
	v_fma_f32 v214, v150, v14, v106
	v_fma_f32 v215, v151, v15, v107
	v_fmac_f32_dpp v212, v12, v156 row_shr:1 row_mask:0xf bank_mask:0xf
	v_fmac_f32_dpp v213, v13, v157 row_shr:1 row_mask:0xf bank_mask:0xf
	v_fmac_f32_dpp v214, v14, v158 row_shr:1 row_mask:0xf bank_mask:0xf
	v_fmac_f32_dpp v215, v15, v159 row_shr:1 row_mask:0xf bank_mask:0xf
	v_fmac_f32_dpp v212, v12, v108 row_shl:1 row_mask:0xf bank_mask:0xf
	v_fmac_f32_dpp v213, v13, v109 row_shl:1 row_mask:0xf bank_mask:0xf
	v_fmac_f32_dpp v214, v14, v110 row_shl:1 row_mask:0xf bank_mask:0xf
	v_fmac_f32_dpp v215, v15, v111 row_shl:1 row_mask:0xf bank_mask:0xf
	v_fmac_f32_dpp v212, v20, v156 row_shl:15 row_mask:0xf bank_mask:0xf
	v_fmac_f32_dpp v213, v21, v157 row_shl:15 row_mask:0xf bank_mask:0xf
	v_fmac_f32_dpp v214, v22, v158 row_shl:15 row_mask:0xf bank_mask:0xf
	v_fmac_f32_dpp v215, v23, v159 row_shl:15 row_mask:0xf bank_mask:0xf
	v_fmac_f32_dpp v212, v8, v108 row_shr:15 row_mask:0xf bank_mask:0xf
	v_fmac_f32_dpp v213, v9, v109 row_shr:15 row_mask:0xf bank_mask:0xf
	v_fmac_f32_dpp v214, v10, v110 row_shr:15 row_mask:0xf bank_mask:0xf
	v_fmac_f32_dpp v215, v11, v111 row_shr:15 row_mask:0xf bank_mask:0xf
	v_mul_f32_e32 v216, 0xbfb8aa3b, v208
	v_mul_f32_e32 v217, 0xbfb8aa3b, v209
	v_mul_f32_e32 v218, 0xbfb8aa3b, v210
	v_mul_f32_e32 v219, 0xbfb8aa3b, v211
	v_exp_f32_e32 v216, v216
	v_exp_f32_e32 v217, v217
	v_exp_f32_e32 v218, v218
	v_exp_f32_e32 v219, v219
	v_add_f32_e32 v216, 1.0, v216
	v_add_f32_e32 v217, 1.0, v217
	v_add_f32_e32 v218, 1.0, v218
	v_add_f32_e32 v219, 1.0, v219
	v_rcp_f32_e32 v216, v216
	v_rcp_f32_e32 v217, v217
	v_rcp_f32_e32 v218, v218
	v_rcp_f32_e32 v219, v219
	v_mul_f32_e32 v208, v208, v216
	v_mul_f32_e32 v209, v209, v217
	v_mul_f32_e32 v210, v210, v218
	v_mul_f32_e32 v211, v211, v219
	v_mul_f32_e32 v208, v208, v212
	v_mul_f32_e32 v209, v209, v213
	v_mul_f32_e32 v210, v210, v214
	v_mul_f32_e32 v211, v211, v215
	v_cvt_pk_bf16_f32 v122, v208, v209
	v_cvt_pk_bf16_f32 v123, v210, v211
	v_mov_b32_e32 v120, v249
	v_mov_b32_e32 v121, v2
	s_add_u32 s4, s6, 0xdc000
	s_addc_u32 s5, s7, 0
	global_store_dwordx4 v244, v[120:123], s[4:5] sc1
	s_waitcnt lgkmcnt(0)
	v_fma_f32 v208, v152, v32, v100
	v_fma_f32 v209, v153, v33, v101
	v_fma_f32 v210, v154, v34, v102
	v_fma_f32 v211, v155, v35, v103
	v_fmac_f32_dpp v208, v32, v160 row_shr:1 row_mask:0xf bank_mask:0xf
	v_fmac_f32_dpp v209, v33, v161 row_shr:1 row_mask:0xf bank_mask:0xf
	v_fmac_f32_dpp v210, v34, v162 row_shr:1 row_mask:0xf bank_mask:0xf
	v_fmac_f32_dpp v211, v35, v163 row_shr:1 row_mask:0xf bank_mask:0xf
	v_fmac_f32_dpp v208, v32, v112 row_shl:1 row_mask:0xf bank_mask:0xf
	v_fmac_f32_dpp v209, v33, v113 row_shl:1 row_mask:0xf bank_mask:0xf
	v_fmac_f32_dpp v210, v34, v114 row_shl:1 row_mask:0xf bank_mask:0xf
	v_fmac_f32_dpp v211, v35, v115 row_shl:1 row_mask:0xf bank_mask:0xf
	v_fmac_f32_dpp v208, v164, v160 row_shl:15 row_mask:0xf bank_mask:0xf
	v_fmac_f32_dpp v209, v165, v161 row_shl:15 row_mask:0xf bank_mask:0xf
	v_fmac_f32_dpp v210, v166, v162 row_shl:15 row_mask:0xf bank_mask:0xf
	v_fmac_f32_dpp v211, v167, v163 row_shl:15 row_mask:0xf bank_mask:0xf
	v_fmac_f32_dpp v208, v24, v112 row_shr:15 row_mask:0xf bank_mask:0xf
	v_fmac_f32_dpp v209, v25, v113 row_shr:15 row_mask:0xf bank_mask:0xf
	v_fmac_f32_dpp v210, v26, v114 row_shr:15 row_mask:0xf bank_mask:0xf
	v_fmac_f32_dpp v211, v27, v115 row_shr:15 row_mask:0xf bank_mask:0xf
	v_fma_f32 v212, v148, v28, v104
	v_fma_f32 v213, v149, v29, v105
	v_fma_f32 v214, v150, v30, v106
	v_fma_f32 v215, v151, v31, v107
	v_fmac_f32_dpp v212, v28, v156 row_shr:1 row_mask:0xf bank_mask:0xf
	v_fmac_f32_dpp v213, v29, v157 row_shr:1 row_mask:0xf bank_mask:0xf
	v_fmac_f32_dpp v214, v30, v158 row_shr:1 row_mask:0xf bank_mask:0xf
	v_fmac_f32_dpp v215, v31, v159 row_shr:1 row_mask:0xf bank_mask:0xf
	v_fmac_f32_dpp v212, v28, v108 row_shl:1 row_mask:0xf bank_mask:0xf
	v_fmac_f32_dpp v213, v29, v109 row_shl:1 row_mask:0xf bank_mask:0xf
	v_fmac_f32_dpp v214, v30, v110 row_shl:1 row_mask:0xf bank_mask:0xf
	v_fmac_f32_dpp v215, v31, v111 row_shl:1 row_mask:0xf bank_mask:0xf
	v_fmac_f32_dpp v212, v168, v156 row_shl:15 row_mask:0xf bank_mask:0xf
	v_fmac_f32_dpp v213, v169, v157 row_shl:15 row_mask:0xf bank_mask:0xf
	v_fmac_f32_dpp v214, v170, v158 row_shl:15 row_mask:0xf bank_mask:0xf
	v_fmac_f32_dpp v215, v171, v159 row_shl:15 row_mask:0xf bank_mask:0xf
	v_fmac_f32_dpp v212, v20, v108 row_shr:15 row_mask:0xf bank_mask:0xf
	v_fmac_f32_dpp v213, v21, v109 row_shr:15 row_mask:0xf bank_mask:0xf
	v_fmac_f32_dpp v214, v22, v110 row_shr:15 row_mask:0xf bank_mask:0xf
	v_fmac_f32_dpp v215, v23, v111 row_shr:15 row_mask:0xf bank_mask:0xf
	ds_read_b128 v[164:167], v223 offset:16
	ds_read_b128 v[168:171], v223 offset:528
	v_mul_f32_e32 v216, 0xbfb8aa3b, v208
	v_mul_f32_e32 v217, 0xbfb8aa3b, v209
	v_mul_f32_e32 v218, 0xbfb8aa3b, v210
	v_mul_f32_e32 v219, 0xbfb8aa3b, v211
	v_exp_f32_e32 v216, v216
	v_exp_f32_e32 v217, v217
	v_exp_f32_e32 v218, v218
	v_exp_f32_e32 v219, v219
	v_add_f32_e32 v216, 1.0, v216
	v_add_f32_e32 v217, 1.0, v217
	v_add_f32_e32 v218, 1.0, v218
	v_add_f32_e32 v219, 1.0, v219
	v_rcp_f32_e32 v216, v216
	v_rcp_f32_e32 v217, v217
	v_rcp_f32_e32 v218, v218
	v_rcp_f32_e32 v219, v219
	v_mul_f32_e32 v208, v208, v216
	v_mul_f32_e32 v209, v209, v217
	v_mul_f32_e32 v210, v210, v218
	v_mul_f32_e32 v211, v211, v219
	v_mul_f32_e32 v208, v208, v212
	v_mul_f32_e32 v209, v209, v213
	v_mul_f32_e32 v210, v210, v214
	v_mul_f32_e32 v211, v211, v215
	v_cvt_pk_bf16_f32 v118, v208, v209
	v_cvt_pk_bf16_f32 v119, v210, v211
	v_mov_b32_e32 v116, v242
	v_mov_b32_e32 v117, v243
	s_add_u32 s4, s6, 0xb0000
	s_addc_u32 s5, s7, 0
	global_store_dwordx4 v244, v[116:119], s[4:5] sc1
	s_waitcnt lgkmcnt(0)
	v_fma_f32 v208, v152, v4, v100
	v_fma_f32 v209, v153, v5, v101
	v_fma_f32 v210, v154, v6, v102
	v_fma_f32 v211, v155, v7, v103
	v_fmac_f32_dpp v208, v4, v160 row_shr:1 row_mask:0xf bank_mask:0xf
	v_fmac_f32_dpp v209, v5, v161 row_shr:1 row_mask:0xf bank_mask:0xf
	v_fmac_f32_dpp v210, v6, v162 row_shr:1 row_mask:0xf bank_mask:0xf
	v_fmac_f32_dpp v211, v7, v163 row_shr:1 row_mask:0xf bank_mask:0xf
	v_fmac_f32_dpp v208, v4, v112 row_shl:1 row_mask:0xf bank_mask:0xf
	v_fmac_f32_dpp v209, v5, v113 row_shl:1 row_mask:0xf bank_mask:0xf
	v_fmac_f32_dpp v210, v6, v114 row_shl:1 row_mask:0xf bank_mask:0xf
	v_fmac_f32_dpp v211, v7, v115 row_shl:1 row_mask:0xf bank_mask:0xf
	v_fmac_f32_dpp v208, v16, v160 row_shl:15 row_mask:0xf bank_mask:0xf
	v_fmac_f32_dpp v209, v17, v161 row_shl:15 row_mask:0xf bank_mask:0xf
	v_fmac_f32_dpp v210, v18, v162 row_shl:15 row_mask:0xf bank_mask:0xf
	v_fmac_f32_dpp v211, v19, v163 row_shl:15 row_mask:0xf bank_mask:0xf
	v_fmac_f32_dpp v208, v164, v112 row_shr:15 row_mask:0xf bank_mask:0xf
	v_fmac_f32_dpp v209, v165, v113 row_shr:15 row_mask:0xf bank_mask:0xf
	v_fmac_f32_dpp v210, v166, v114 row_shr:15 row_mask:0xf bank_mask:0xf
	v_fmac_f32_dpp v211, v167, v115 row_shr:15 row_mask:0xf bank_mask:0xf
	v_fma_f32 v212, v148, v8, v104
	v_fma_f32 v213, v149, v9, v105
	v_fma_f32 v214, v150, v10, v106
	v_fma_f32 v215, v151, v11, v107
	v_fmac_f32_dpp v212, v8, v156 row_shr:1 row_mask:0xf bank_mask:0xf
	v_fmac_f32_dpp v213, v9, v157 row_shr:1 row_mask:0xf bank_mask:0xf
	v_fmac_f32_dpp v214, v10, v158 row_shr:1 row_mask:0xf bank_mask:0xf
	v_fmac_f32_dpp v215, v11, v159 row_shr:1 row_mask:0xf bank_mask:0xf
	v_fmac_f32_dpp v212, v8, v108 row_shl:1 row_mask:0xf bank_mask:0xf
	v_fmac_f32_dpp v213, v9, v109 row_shl:1 row_mask:0xf bank_mask:0xf
	v_fmac_f32_dpp v214, v10, v110 row_shl:1 row_mask:0xf bank_mask:0xf
	v_fmac_f32_dpp v215, v11, v111 row_shl:1 row_mask:0xf bank_mask:0xf
	v_fmac_f32_dpp v212, v12, v156 row_shl:15 row_mask:0xf bank_mask:0xf
	v_fmac_f32_dpp v213, v13, v157 row_shl:15 row_mask:0xf bank_mask:0xf
	v_fmac_f32_dpp v214, v14, v158 row_shl:15 row_mask:0xf bank_mask:0xf
	v_fmac_f32_dpp v215, v15, v159 row_shl:15 row_mask:0xf bank_mask:0xf
	v_fmac_f32_dpp v212, v168, v108 row_shr:15 row_mask:0xf bank_mask:0xf
	v_fmac_f32_dpp v213, v169, v109 row_shr:15 row_mask:0xf bank_mask:0xf
	v_fmac_f32_dpp v214, v170, v110 row_shr:15 row_mask:0xf bank_mask:0xf
	v_fmac_f32_dpp v215, v171, v111 row_shr:15 row_mask:0xf bank_mask:0xf
	v_mul_f32_e32 v216, 0xbfb8aa3b, v208
	v_mul_f32_e32 v217, 0xbfb8aa3b, v209
	v_mul_f32_e32 v218, 0xbfb8aa3b, v210
	v_mul_f32_e32 v219, 0xbfb8aa3b, v211
	v_exp_f32_e32 v216, v216
	v_exp_f32_e32 v217, v217
	v_exp_f32_e32 v218, v218
	v_exp_f32_e32 v219, v219
	v_add_f32_e32 v216, 1.0, v216
	v_add_f32_e32 v217, 1.0, v217
	v_add_f32_e32 v218, 1.0, v218
	v_add_f32_e32 v219, 1.0, v219
	v_rcp_f32_e32 v216, v216
	v_rcp_f32_e32 v217, v217
	v_rcp_f32_e32 v218, v218
	v_rcp_f32_e32 v219, v219
	v_mul_f32_e32 v208, v208, v216
	v_mul_f32_e32 v209, v209, v217
	v_mul_f32_e32 v210, v210, v218
	v_mul_f32_e32 v211, v211, v219
	v_mul_f32_e32 v208, v208, v212
	v_mul_f32_e32 v209, v209, v213
	v_mul_f32_e32 v210, v210, v214
	v_mul_f32_e32 v211, v211, v215
	v_cvt_pk_bf16_f32 v122, v208, v209
	v_cvt_pk_bf16_f32 v123, v210, v211
	v_mov_b32_e32 v120, v206
	v_mov_b32_e32 v121, v207
	s_add_u32 s4, s6, 0xf2000
	s_addc_u32 s5, s7, 0
	s_cmp_eq_u32 s98, 1
	s_cselect_b32 s99, 0x7fff7fff, -1
	s_mov_b32 exec_lo, s99
	s_mov_b32 exec_hi, s99
	global_store_dwordx4 v244, v[120:123], s[4:5] sc1
	s_mov_b64 exec, -1
	s_mov_b64 s[4:5], -1
	s_cmp_eq_u32 s98, 0
	s_cselect_b64 s[8:9], 0, -1
	s_cbranch_scc1 .Lce_nobar1
	s_barrier
